# v058 + rope-part (k_pe/q_pe) LDS reads issued ahead of the QK^T MFMAs in all four loop copies
# speedup vs baseline: 1.0043x; 1.0004x over previous
.LBB0_738:
	s_cmp_lt_u32 s78, 4
	s_cbranch_scc0 .Latt1_738
	v_readfirstlane_b32 s16, v134
	v_readfirstlane_b32 s17, v135
	s_lshl_b32 s3, s78, 10
	s_add_u32 s16, s16, 0x33080000
	s_addc_u32 s17, s17, 0
	s_add_i32 m0, s3, 0x8000
	s_nop 0
	global_load_lds_dwordx4 v166, s[16:17]
	s_add_u32 s16, s16, 0x20000
	s_addc_u32 s17, s17, 0
	s_add_i32 m0, s3, 0xa000
	s_nop 0
	global_load_lds_dwordx4 v166, s[16:17]
	v_readfirstlane_b32 s16, v132
	v_readfirstlane_b32 s17, v133
	s_add_u32 s16, s16, 0x2f804000
	s_addc_u32 s17, s17, 0
	s_add_i32 m0, s3, 0x10000
	s_nop 0
	global_load_lds_dwordx4 v168, s[16:17]
	v_readfirstlane_b32 s16, v134
	v_readfirstlane_b32 s17, v135
	s_lshl_b32 s3, s78, 14
	s_sub_u32 s16, s16, s3
	s_subb_u32 s17, s17, 0
	s_add_u32 s16, s16, 0x33040100
	s_addc_u32 s17, s17, 0
	s_lshl_b32 s3, s78, 10
	s_add_i32 m0, s3, 0x4000
	s_nop 0
	global_load_lds_dwordx4 v167, s[16:17]
	s_add_u32 s16, s16, 0x20000
	s_addc_u32 s17, s17, 0
	s_add_i32 m0, s3, 0x6000
	s_nop 0
	global_load_lds_dwordx4 v167, s[16:17]
	s_add_i32 s2, s26, -1
	ds_read_b128 v[64:67], v170 offset:49152
	ds_read_b128 v[68:71], v170 offset:57344
	ds_read_b128 v[154:157], v171 offset:49152
	ds_read_b128 v[202:205], v171 offset:57344
	ds_read_b128 v[224:227], v172 offset:49152
	ds_read_b128 v[228:231], v172 offset:57344
	s_add_i32 s3, 0, 0x12000
	v_add_u32_e32 v189, s3, v178
	v_add_u32_e32 v190, s3, v180
	v_add_u32_e32 v191, s3, v182
	v_add_u32_e32 v192, s3, v184
	s_cmp_gt_u32 s2, s27
	s_cselect_b64 vcc, -1, 0
	s_waitcnt lgkmcnt(5)
	v_mfma_f32_32x32x16_bf16 v[80:95], v[64:67], v[126:129], 0
	s_waitcnt lgkmcnt(4)
	v_mfma_f32_32x32x16_bf16 v[64:79], v[68:71], v[126:129], 0
	s_waitcnt lgkmcnt(3)
	v_mfma_f32_32x32x16_bf16 v[80:95], v[154:157], v[122:125], v[80:95]
	ds_read_b128 v[154:157], v173 offset:49152
	s_waitcnt lgkmcnt(3)
	v_mfma_f32_32x32x16_bf16 v[64:79], v[202:205], v[122:125], v[64:79]
	ds_read_b128 v[202:205], v173 offset:57344
	s_waitcnt lgkmcnt(3)
	v_mfma_f32_32x32x16_bf16 v[80:95], v[224:227], v[118:121], v[80:95]
	ds_read_b128 v[224:227], v174 offset:49152
	s_waitcnt lgkmcnt(3)
	v_mfma_f32_32x32x16_bf16 v[64:79], v[228:231], v[118:121], v[64:79]
	ds_read_b128 v[228:231], v174 offset:57344
	s_waitcnt lgkmcnt(3)
	v_mfma_f32_32x32x16_bf16 v[80:95], v[154:157], v[114:117], v[80:95]
	ds_read_b128 v[154:157], v175 offset:49152
	s_waitcnt lgkmcnt(3)
	v_mfma_f32_32x32x16_bf16 v[64:79], v[202:205], v[114:117], v[64:79]
	ds_read_b128 v[202:205], v175 offset:57344
	s_waitcnt lgkmcnt(3)
	v_mfma_f32_32x32x16_bf16 v[80:95], v[224:227], v[110:113], v[80:95]
	ds_read_b128 v[224:227], v176 offset:49152
	s_waitcnt lgkmcnt(3)
	v_mfma_f32_32x32x16_bf16 v[64:79], v[228:231], v[110:113], v[64:79]
	ds_read_b128 v[228:231], v176 offset:57344
	s_waitcnt lgkmcnt(3)
	v_mfma_f32_32x32x16_bf16 v[80:95], v[154:157], v[106:109], v[80:95]
	ds_read_b128 v[154:157], v177 offset:49152
	s_waitcnt lgkmcnt(3)
	v_mfma_f32_32x32x16_bf16 v[64:79], v[202:205], v[106:109], v[64:79]
	ds_read_b128 v[202:205], v177 offset:57344
	s_waitcnt lgkmcnt(3)
	v_mfma_f32_32x32x16_bf16 v[80:95], v[224:227], v[102:105], v[80:95]
	ds_read_b128 v[232:235], v189
	ds_read_b128 v[236:239], v189 offset:4096
	ds_read_b128 v[240:243], v163
	s_waitcnt lgkmcnt(5)
	v_mfma_f32_32x32x16_bf16 v[64:79], v[228:231], v[102:105], v[64:79]
	s_waitcnt lgkmcnt(4)
	v_mfma_f32_32x32x16_bf16 v[80:95], v[154:157], v[98:101], v[80:95]
	ds_read_b128 v[224:227], v190
	ds_read_b128 v[228:231], v190 offset:4096
	ds_read_b128 v[154:157], v163 offset:1024
	s_waitcnt lgkmcnt(6)
	v_mfma_f32_32x32x16_bf16 v[64:79], v[202:205], v[98:101], v[64:79]
	s_waitcnt lgkmcnt(3)
	v_mfma_f32_32x32x16_bf16 v[80:95], v[232:235], v[240:243], v[80:95]
	s_waitcnt lgkmcnt(3)
	v_mfma_f32_32x32x16_bf16 v[64:79], v[236:239], v[240:243], v[64:79]
	ds_read_b128 v[232:235], v191
	ds_read_b128 v[236:239], v191 offset:4096
	ds_read_b128 v[240:243], v163 offset:2048
	s_waitcnt lgkmcnt(3)
	v_mfma_f32_32x32x16_bf16 v[80:95], v[224:227], v[154:157], v[80:95]
	s_waitcnt lgkmcnt(3)
	v_mfma_f32_32x32x16_bf16 v[64:79], v[228:231], v[154:157], v[64:79]
	ds_read_b128 v[224:227], v192
	ds_read_b128 v[228:231], v192 offset:4096
	ds_read_b128 v[154:157], v163 offset:3072
	s_waitcnt lgkmcnt(3)
	v_mfma_f32_32x32x16_bf16 v[80:95], v[232:235], v[240:243], v[80:95]
	s_waitcnt lgkmcnt(3)
	v_mfma_f32_32x32x16_bf16 v[64:79], v[236:239], v[240:243], v[64:79]
	s_waitcnt lgkmcnt(0)
	v_mfma_f32_32x32x16_bf16 v[80:95], v[224:227], v[154:157], v[80:95]
	s_waitcnt lgkmcnt(0)
	v_mfma_f32_32x32x16_bf16 v[64:79], v[228:231], v[154:157], v[64:79]
	s_nop 10
	v_cndmask_b32_e32 v240, v80, v208, vcc
	v_add_f32_e32 v80, 0, v220
	v_add_f32_e32 v80, v222, v80
	v_add_f32_e32 v80, v218, v80
	v_add_f32_e32 v80, v221, v80
	v_add_f32_e32 v80, v216, v80
	v_add_f32_e32 v80, v219, v80
	v_add_f32_e32 v80, v215, v80
	v_add_f32_e32 v80, v217, v80
	v_add_f32_e32 v80, v212, v80
	v_add_f32_e32 v80, v214, v80
	v_add_f32_e32 v80, v210, v80
	v_add_f32_e32 v80, v213, v80
	v_cndmask_b32_e32 v244, v64, v208, vcc
	v_exp_f32_e32 v64, v148
	v_add_f32_e32 v80, v198, v80
	v_cndmask_b32_e32 v245, v65, v208, vcc
	v_exp_f32_e32 v65, v149
	v_add_f32_e32 v80, v211, v80
	v_cndmask_b32_e32 v242, v66, v208, vcc
	v_exp_f32_e32 v66, v146
	v_add_f32_e32 v80, v197, v80
	v_cndmask_b32_e32 v243, v67, v208, vcc
	v_exp_f32_e32 v67, v147
	v_add_f32_e32 v80, v199, v80
	v_cndmask_b32_e32 v238, v68, v208, vcc
	v_exp_f32_e32 v68, v144
	v_add_f32_e32 v80, v64, v80
	v_cndmask_b32_e32 v239, v69, v208, vcc
	v_exp_f32_e32 v69, v145
	v_add_f32_e32 v80, v65, v80
	v_cndmask_b32_e32 v234, v70, v208, vcc
	v_exp_f32_e32 v70, v140
	v_add_f32_e32 v80, v66, v80
	v_cndmask_b32_e32 v235, v71, v208, vcc
	v_exp_f32_e32 v71, v141
	v_add_f32_e32 v80, v67, v80
	v_cndmask_b32_e32 v230, v72, v208, vcc
	v_exp_f32_e32 v72, v138
	v_add_f32_e32 v80, v68, v80
	v_cndmask_b32_e32 v231, v73, v208, vcc
	v_exp_f32_e32 v73, v139
	v_add_f32_e32 v80, v69, v80
	v_cndmask_b32_e32 v227, v74, v208, vcc
	v_exp_f32_e32 v74, v152
	v_add_f32_e32 v80, v70, v80
	v_cndmask_b32_e32 v228, v75, v208, vcc
	v_exp_f32_e32 v75, v153
	v_add_f32_e32 v80, v71, v80
	v_cndmask_b32_e32 v225, v76, v208, vcc
	v_exp_f32_e32 v76, v150
	v_add_f32_e32 v80, v72, v80
	v_cndmask_b32_e32 v195, v90, v208, vcc
	v_cndmask_b32_e32 v90, v77, v208, vcc
	v_exp_f32_e32 v77, v151
	v_add_f32_e32 v80, v73, v80
	v_cndmask_b32_e32 v223, v88, v208, vcc
	v_cndmask_b32_e32 v88, v78, v208, vcc
	v_exp_f32_e32 v78, v142
	v_add_f32_e32 v80, v74, v80
	v_cndmask_b32_e32 v224, v89, v208, vcc
	v_cndmask_b32_e32 v89, v79, v208, vcc
	v_exp_f32_e32 v79, v143
	v_add_f32_e32 v80, v75, v80
	v_add_f32_e32 v80, v76, v80
	v_add_f32_e32 v80, v77, v80
	v_add_f32_e32 v80, v78, v80
	v_add_f32_e32 v193, v79, v80
	v_cndmask_b32_e32 v226, v86, v208, vcc
	v_cndmask_b32_e32 v232, v84, v208, vcc
	v_cndmask_b32_e32 v233, v85, v208, vcc
	v_mov_b32_e32 v194, v193
	v_cvt_pk_bf16_f32 v84, v220, v222
	v_cvt_pk_bf16_f32 v85, v218, v221
	v_cvt_pk_bf16_f32 v86, v216, v219
	v_cndmask_b32_e32 v94, v94, v208, vcc
	v_cndmask_b32_e32 v95, v95, v208, vcc
	v_cndmask_b32_e32 v92, v92, v208, vcc
	v_cndmask_b32_e32 v93, v93, v208, vcc
	v_cndmask_b32_e32 v91, v91, v208, vcc
	v_cndmask_b32_e32 v229, v87, v208, vcc
	v_cndmask_b32_e32 v236, v82, v208, vcc
	v_cndmask_b32_e32 v237, v83, v208, vcc
	v_cndmask_b32_e32 v241, v81, v208, vcc
	v_permlane32_swap_b32_e32 v193, v194
	v_cvt_pk_bf16_f32 v87, v215, v217
	v_permlane32_swap_b32_e32 v84, v86
	v_cvt_pk_bf16_f32 v142, v212, v214
	v_cvt_pk_bf16_f32 v143, v210, v213
	v_cvt_pk_bf16_f32 v144, v198, v211
	v_cvt_pk_bf16_f32 v145, v197, v199
	v_cvt_pk_bf16_f32 v146, v64, v65
	v_cvt_pk_bf16_f32 v147, v66, v67
	v_cvt_pk_bf16_f32 v148, v68, v69
	v_cvt_pk_bf16_f32 v149, v70, v71
	v_cvt_pk_bf16_f32 v150, v72, v73
	v_cvt_pk_bf16_f32 v151, v74, v75
	v_cvt_pk_bf16_f32 v152, v76, v77
	v_cvt_pk_bf16_f32 v153, v78, v79
	v_permlane32_swap_b32_e32 v85, v87
	v_permlane32_swap_b32_e32 v142, v144
	v_permlane32_swap_b32_e32 v143, v145
	v_permlane32_swap_b32_e32 v146, v148
	v_permlane32_swap_b32_e32 v147, v149
	v_permlane32_swap_b32_e32 v150, v152
	v_permlane32_swap_b32_e32 v151, v153
	ds_read_b64_tr_b16 v[154:155], v164 offset:0
	ds_read_b64_tr_b16 v[156:157], v164 offset:0x800
	ds_read_b64_tr_b16 v[196:197], v164 offset:0x1000
	ds_read_b64_tr_b16 v[198:199], v164 offset:0x1800
	ds_read_b64_tr_b16 v[202:203], v164 offset:0x2000
	ds_read_b64_tr_b16 v[204:205], v164 offset:0x2800
	ds_read_b64_tr_b16 v[210:211], v164 offset:0x3000
	ds_read_b64_tr_b16 v[212:213], v164 offset:0x3800
	s_waitcnt lgkmcnt(0)
	s_nop 0
	v_mfma_f32_32x32x16_bf16 v[0:15], v[84:87], v[154:157], v[0:15]
	ds_read_b64_tr_b16 v[154:155], v164 offset:0x200
	ds_read_b64_tr_b16 v[156:157], v164 offset:0xa00
	v_mfma_f32_32x32x16_bf16 v[0:15], v[142:145], v[196:199], v[0:15]
	ds_read_b64_tr_b16 v[196:197], v164 offset:0x1200
	ds_read_b64_tr_b16 v[198:199], v164 offset:0x1a00
	v_mfma_f32_32x32x16_bf16 v[0:15], v[146:149], v[202:205], v[0:15]
	ds_read_b64_tr_b16 v[202:203], v164 offset:0x2200
	ds_read_b64_tr_b16 v[204:205], v164 offset:0x2a00
	v_mfma_f32_32x32x16_bf16 v[0:15], v[150:153], v[210:213], v[0:15]
	ds_read_b64_tr_b16 v[210:211], v164 offset:0x3200
	ds_read_b64_tr_b16 v[212:213], v164 offset:0x3a00
	s_waitcnt lgkmcnt(0)
	v_mfma_f32_32x32x16_bf16 v[48:63], v[84:87], v[154:157], v[48:63]
	ds_read_b64_tr_b16 v[154:155], v164 offset:0x400
	ds_read_b64_tr_b16 v[156:157], v164 offset:0xc00
	v_mfma_f32_32x32x16_bf16 v[48:63], v[142:145], v[196:199], v[48:63]
	ds_read_b64_tr_b16 v[196:197], v164 offset:0x1400
	ds_read_b64_tr_b16 v[198:199], v164 offset:0x1c00
	v_mfma_f32_32x32x16_bf16 v[48:63], v[146:149], v[202:205], v[48:63]
	ds_read_b64_tr_b16 v[202:203], v164 offset:0x2400
	ds_read_b64_tr_b16 v[204:205], v164 offset:0x2c00
	v_mfma_f32_32x32x16_bf16 v[48:63], v[150:153], v[210:213], v[48:63]
	ds_read_b64_tr_b16 v[210:211], v164 offset:0x3400
	ds_read_b64_tr_b16 v[212:213], v164 offset:0x3c00
	s_waitcnt lgkmcnt(0)
	v_mfma_f32_32x32x16_bf16 v[32:47], v[84:87], v[154:157], v[32:47]
	ds_read_b64_tr_b16 v[154:155], v164 offset:0x600
	ds_read_b64_tr_b16 v[156:157], v164 offset:0xe00
	v_mfma_f32_32x32x16_bf16 v[32:47], v[142:145], v[196:199], v[32:47]
	ds_read_b64_tr_b16 v[196:197], v164 offset:0x1600
	ds_read_b64_tr_b16 v[198:199], v164 offset:0x1e00
	v_mfma_f32_32x32x16_bf16 v[32:47], v[146:149], v[202:205], v[32:47]
	ds_read_b64_tr_b16 v[202:203], v164 offset:0x2600
	ds_read_b64_tr_b16 v[204:205], v164 offset:0x2e00
	v_mfma_f32_32x32x16_bf16 v[32:47], v[150:153], v[210:213], v[32:47]
	ds_read_b64_tr_b16 v[210:211], v164 offset:0x3600
	ds_read_b64_tr_b16 v[212:213], v164 offset:0x3e00
	s_waitcnt lgkmcnt(0)
	v_mfma_f32_32x32x16_bf16 v[16:31], v[84:87], v[154:157], v[16:31]
	v_max_f32_e32 v84, v241, v241
	v_max_f32_e32 v85, v240, v240
	v_max_f32_e32 v84, v85, v84
	v_max3_f32 v84, v84, v236, v237
	v_max3_f32 v84, v84, v232, v233
	v_max3_f32 v84, v84, v226, v229
	v_max3_f32 v84, v84, v223, v224
	v_mfma_f32_32x32x16_bf16 v[16:31], v[142:145], v[196:199], v[16:31]
	v_max3_f32 v84, v84, v195, v91
	v_max3_f32 v84, v84, v92, v93
	v_max3_f32 v84, v84, v94, v95
	v_max3_f32 v84, v84, v244, v245
	v_max3_f32 v84, v84, v242, v243
	v_max3_f32 v84, v84, v238, v239
	v_max3_f32 v84, v84, v234, v235
	v_mfma_f32_32x32x16_bf16 v[16:31], v[146:149], v[202:205], v[16:31]
	v_max3_f32 v84, v84, v230, v231
	v_max3_f32 v84, v84, v227, v228
	v_max3_f32 v84, v84, v225, v90
	v_max3_f32 v84, v84, v88, v89
	v_mov_b32_e32 v85, v84
	s_nop 1
	v_permlane32_swap_b32_e32 v84, v85
	v_mfma_f32_32x32x16_bf16 v[16:31], v[150:153], v[210:213], v[16:31]
	v_max_f32_e32 v85, v85, v85
	v_max_f32_e32 v84, v84, v84
	v_max_f32_e32 v84, v84, v85
	v_sub_f32_e32 v85, v84, v165
	v_cmp_ge_f32_e32 vcc, s21, v85
	v_mov_b32_e32 v196, 1.0
	s_cmp_eq_u64 vcc, exec
	s_cbranch_scc0 .LBB0_750

.LBB0_743:
	v_mul_f32_e32 v136, 0xbdd53b94, v165
	v_fmamk_f32 v78, v94, 0x3dd53b94, v136
	v_fmamk_f32 v74, v195, 0x3dd53b94, v136
	v_exp_f32_e32 v195, v78
	v_fmamk_f32 v64, v240, 0x3dd53b94, v136
	v_fmamk_f32 v65, v241, 0x3dd53b94, v136
	v_fmamk_f32 v66, v236, 0x3dd53b94, v136
	v_fmamk_f32 v67, v237, 0x3dd53b94, v136
	v_fmamk_f32 v68, v232, 0x3dd53b94, v136
	v_fmamk_f32 v69, v233, 0x3dd53b94, v136
	v_fmamk_f32 v70, v226, 0x3dd53b94, v136
	v_fmamk_f32 v71, v229, 0x3dd53b94, v136
	v_fmamk_f32 v72, v223, 0x3dd53b94, v136
	v_fmamk_f32 v73, v224, 0x3dd53b94, v136
	v_fmamk_f32 v75, v91, 0x3dd53b94, v136
	v_fmamk_f32 v76, v92, 0x3dd53b94, v136
	v_fmamk_f32 v77, v93, 0x3dd53b94, v136
	v_fmamk_f32 v79, v95, 0x3dd53b94, v136
	v_fmamk_f32 v223, v244, 0x3dd53b94, v136
	v_fmamk_f32 v224, v245, 0x3dd53b94, v136
	v_fmamk_f32 v236, v242, 0x3dd53b94, v136
	v_fmamk_f32 v237, v243, 0x3dd53b94, v136
	v_fmamk_f32 v238, v238, 0x3dd53b94, v136
	v_fmamk_f32 v239, v239, 0x3dd53b94, v136
	v_fmamk_f32 v240, v234, 0x3dd53b94, v136
	v_fmamk_f32 v241, v235, 0x3dd53b94, v136
	v_fmamk_f32 v242, v230, 0x3dd53b94, v136
	v_fmamk_f32 v243, v231, 0x3dd53b94, v136
	v_fmamk_f32 v244, v227, 0x3dd53b94, v136
	v_fmamk_f32 v245, v228, 0x3dd53b94, v136
	v_fmamk_f32 v246, v225, 0x3dd53b94, v136
	v_exp_f32_e32 v233, v64
	v_exp_f32_e32 v235, v65
	v_exp_f32_e32 v231, v66
	v_exp_f32_e32 v234, v67
	v_exp_f32_e32 v229, v68
	v_exp_f32_e32 v232, v69
	v_exp_f32_e32 v228, v70
	v_exp_f32_e32 v230, v71
	v_exp_f32_e32 v225, v72
	v_exp_f32_e32 v227, v73
	v_exp_f32_e32 v221, v74
	v_exp_f32_e32 v226, v75
	v_exp_f32_e32 v219, v76
	v_exp_f32_e32 v222, v77
	v_exp_f32_e32 v220, v79
	v_fmamk_f32 v247, v90, 0x3dd53b94, v136
	v_fmamk_f32 v248, v88, 0x3dd53b94, v136
	v_fmamk_f32 v202, v89, 0x3dd53b94, v136
	s_waitcnt vmcnt(0) lgkmcnt(0)
	s_barrier
	v_readfirstlane_b32 s16, v134
	v_readfirstlane_b32 s17, v135
	s_lshl_b32 s3, s78, 10
	s_add_u32 s16, s16, 0x330c0000
	s_addc_u32 s17, s17, 0
	s_add_i32 m0, s3, 0xc000
	s_nop 0
	global_load_lds_dwordx4 v166, s[16:17]
	s_add_u32 s16, s16, 0x20000
	s_addc_u32 s17, s17, 0
	s_add_i32 m0, s3, 0xe000
	s_nop 0
	global_load_lds_dwordx4 v166, s[16:17]
	v_readfirstlane_b32 s16, v132
	v_readfirstlane_b32 s17, v133
	s_add_u32 s16, s16, 0x2f806000
	s_addc_u32 s17, s17, 0
	s_add_i32 m0, s3, 0x12000
	s_nop 0
	global_load_lds_dwordx4 v168, s[16:17]
	v_readfirstlane_b32 s16, v134
	v_readfirstlane_b32 s17, v135
	s_lshl_b32 s3, s78, 14
	s_sub_u32 s16, s16, s3
	s_subb_u32 s17, s17, 0
	s_add_u32 s16, s16, 0x33080100
	s_addc_u32 s17, s17, 0
	s_lshl_b32 s3, s78, 10
	s_add_i32 m0, s3, 0x0
	s_nop 0
	global_load_lds_dwordx4 v167, s[16:17]
	s_add_u32 s16, s16, 0x20000
	s_addc_u32 s17, s17, 0
	s_add_i32 m0, s3, 0x2000
	s_nop 0
	global_load_lds_dwordx4 v167, s[16:17]
	ds_read_b128 v[64:67], v170 offset:32768
	ds_read_b128 v[68:71], v170 offset:40960
	ds_read_b128 v[142:145], v171 offset:32768
	ds_read_b128 v[146:149], v171 offset:40960
	ds_read_b128 v[150:153], v172 offset:32768
	s_cmp_lt_u32 s2, s27
	s_cselect_b64 vcc, -1, 0
	s_waitcnt lgkmcnt(4)
	v_mfma_f32_32x32x16_bf16 v[80:95], v[64:67], v[126:129], 0
	s_waitcnt lgkmcnt(3)
	v_mfma_f32_32x32x16_bf16 v[64:79], v[68:71], v[126:129], 0
	s_waitcnt lgkmcnt(2)
	v_mfma_f32_32x32x16_bf16 v[80:95], v[142:145], v[122:125], v[80:95]
	ds_read_b128 v[142:145], v172 offset:40960
	s_waitcnt lgkmcnt(2)
	v_mfma_f32_32x32x16_bf16 v[64:79], v[146:149], v[122:125], v[64:79]
	ds_read_b128 v[146:149], v173 offset:32768
	s_waitcnt lgkmcnt(2)
	v_mfma_f32_32x32x16_bf16 v[80:95], v[150:153], v[118:121], v[80:95]
	ds_read_b128 v[150:153], v173 offset:40960
	s_waitcnt lgkmcnt(2)
	v_mfma_f32_32x32x16_bf16 v[64:79], v[142:145], v[118:121], v[64:79]
	ds_read_b128 v[142:145], v174 offset:32768
	s_waitcnt lgkmcnt(2)
	v_mfma_f32_32x32x16_bf16 v[80:95], v[146:149], v[114:117], v[80:95]
	ds_read_b128 v[146:149], v174 offset:40960
	s_waitcnt lgkmcnt(2)
	v_mfma_f32_32x32x16_bf16 v[64:79], v[150:153], v[114:117], v[64:79]
	ds_read_b128 v[150:153], v175 offset:32768
	s_waitcnt lgkmcnt(2)
	v_mfma_f32_32x32x16_bf16 v[80:95], v[142:145], v[110:113], v[80:95]
	ds_read_b128 v[142:145], v175 offset:40960
	s_waitcnt lgkmcnt(2)
	v_mfma_f32_32x32x16_bf16 v[64:79], v[146:149], v[110:113], v[64:79]
	ds_read_b128 v[146:149], v176 offset:32768
	s_waitcnt lgkmcnt(2)
	v_mfma_f32_32x32x16_bf16 v[80:95], v[150:153], v[106:109], v[80:95]
	ds_read_b128 v[150:153], v176 offset:40960
	s_waitcnt lgkmcnt(2)
	v_mfma_f32_32x32x16_bf16 v[64:79], v[142:145], v[106:109], v[64:79]
	ds_read_b128 v[142:145], v177 offset:32768
	s_waitcnt lgkmcnt(2)
	v_mfma_f32_32x32x16_bf16 v[80:95], v[146:149], v[102:105], v[80:95]
	ds_read_b128 v[146:149], v177 offset:40960
	s_waitcnt lgkmcnt(2)
	v_mfma_f32_32x32x16_bf16 v[64:79], v[150:153], v[102:105], v[64:79]
	ds_read_b128 v[210:213], v179
	ds_read_b128 v[214:217], v179 offset:4096
	ds_read_b128 v[150:153], v163
	s_waitcnt lgkmcnt(4)
	v_mfma_f32_32x32x16_bf16 v[80:95], v[142:145], v[98:101], v[80:95]
	s_waitcnt lgkmcnt(3)
	v_mfma_f32_32x32x16_bf16 v[64:79], v[146:149], v[98:101], v[64:79]
	ds_read_b128 v[142:145], v181
	ds_read_b128 v[146:149], v181 offset:4096
	s_waitcnt lgkmcnt(2)
	v_mfma_f32_32x32x16_bf16 v[80:95], v[210:213], v[150:153], v[80:95]
	s_waitcnt lgkmcnt(2)
	v_mfma_f32_32x32x16_bf16 v[64:79], v[214:217], v[150:153], v[64:79]
	ds_read_b128 v[150:153], v163 offset:1024
	ds_read_b128 v[210:213], v183
	ds_read_b128 v[214:217], v183 offset:4096
	s_waitcnt lgkmcnt(2)
	v_mfma_f32_32x32x16_bf16 v[80:95], v[142:145], v[150:153], v[80:95]
	s_waitcnt lgkmcnt(2)
	v_mfma_f32_32x32x16_bf16 v[64:79], v[146:149], v[150:153], v[64:79]
	ds_read_b128 v[150:153], v163 offset:2048
	ds_read_b128 v[142:145], v185
	ds_read_b128 v[146:149], v185 offset:4096
	s_waitcnt lgkmcnt(2)
	v_mfma_f32_32x32x16_bf16 v[80:95], v[210:213], v[150:153], v[80:95]
	s_waitcnt lgkmcnt(2)
	v_mfma_f32_32x32x16_bf16 v[64:79], v[214:217], v[150:153], v[64:79]
	ds_read_b128 v[150:153], v163 offset:3072
	s_waitcnt lgkmcnt(0)
	v_mfma_f32_32x32x16_bf16 v[80:95], v[142:145], v[150:153], v[80:95]
	s_waitcnt lgkmcnt(0)
	v_mfma_f32_32x32x16_bf16 v[64:79], v[146:149], v[150:153], v[64:79]
	s_nop 10
	v_cndmask_b32_e32 v218, v208, v80, vcc
	v_add_f32_e32 v80, 0, v233
	v_add_f32_e32 v80, v235, v80
	v_add_f32_e32 v80, v231, v80
	v_add_f32_e32 v80, v234, v80
	v_add_f32_e32 v80, v229, v80
	v_add_f32_e32 v80, v232, v80
	v_add_f32_e32 v80, v228, v80
	v_add_f32_e32 v80, v230, v80
	v_add_f32_e32 v80, v225, v80
	v_add_f32_e32 v80, v227, v80
	v_add_f32_e32 v80, v221, v80
	v_add_f32_e32 v80, v226, v80
	v_cndmask_b32_e32 v148, v208, v64, vcc
	v_exp_f32_e32 v64, v223
	v_add_f32_e32 v80, v219, v80
	v_cndmask_b32_e32 v149, v208, v65, vcc
	v_exp_f32_e32 v65, v224
	v_add_f32_e32 v80, v222, v80
	v_cndmask_b32_e32 v146, v208, v66, vcc
	v_exp_f32_e32 v66, v236
	v_add_f32_e32 v80, v195, v80
	v_cndmask_b32_e32 v147, v208, v67, vcc
	v_exp_f32_e32 v67, v237
	v_add_f32_e32 v80, v220, v80
	v_cndmask_b32_e32 v144, v208, v68, vcc
	v_exp_f32_e32 v68, v238
	v_add_f32_e32 v80, v64, v80
	v_cndmask_b32_e32 v145, v208, v69, vcc
	v_exp_f32_e32 v69, v239
	v_add_f32_e32 v80, v65, v80
	v_cndmask_b32_e32 v142, v208, v70, vcc
	v_exp_f32_e32 v70, v240
	v_add_f32_e32 v80, v66, v80
	v_cndmask_b32_e32 v143, v208, v71, vcc
	v_exp_f32_e32 v71, v241
	v_add_f32_e32 v80, v67, v80
	v_cndmask_b32_e32 v151, v208, v94, vcc
	v_cndmask_b32_e32 v94, v208, v72, vcc
	v_exp_f32_e32 v72, v242
	v_add_f32_e32 v80, v68, v80
	v_cndmask_b32_e32 v150, v208, v95, vcc
	v_cndmask_b32_e32 v95, v208, v73, vcc
	v_exp_f32_e32 v73, v243
	v_add_f32_e32 v80, v69, v80
	v_cndmask_b32_e32 v153, v208, v92, vcc
	v_cndmask_b32_e32 v92, v208, v74, vcc
	v_exp_f32_e32 v74, v244
	v_add_f32_e32 v80, v70, v80
	v_cndmask_b32_e32 v152, v208, v93, vcc
	v_cndmask_b32_e32 v93, v208, v75, vcc
	v_exp_f32_e32 v75, v245
	v_add_f32_e32 v80, v71, v80
	v_cndmask_b32_e32 v198, v208, v90, vcc
	v_cndmask_b32_e32 v90, v208, v76, vcc
	v_exp_f32_e32 v76, v246
	v_add_f32_e32 v80, v72, v80
	v_cndmask_b32_e32 v197, v208, v91, vcc
	v_cndmask_b32_e32 v91, v208, v77, vcc
	v_exp_f32_e32 v77, v247
	v_add_f32_e32 v80, v73, v80
	v_cndmask_b32_e32 v210, v208, v88, vcc
	v_cndmask_b32_e32 v88, v208, v78, vcc
	v_exp_f32_e32 v78, v248
	v_add_f32_e32 v80, v74, v80
	v_cndmask_b32_e32 v199, v208, v89, vcc
	v_cndmask_b32_e32 v89, v208, v79, vcc
	v_exp_f32_e32 v79, v202
	v_add_f32_e32 v80, v75, v80
	v_add_f32_e32 v80, v76, v80
	v_add_f32_e32 v80, v77, v80
	v_add_f32_e32 v80, v78, v80
	v_add_f32_e32 v223, v79, v80
	v_cndmask_b32_e32 v212, v208, v86, vcc
	v_cndmask_b32_e32 v213, v208, v85, vcc
	v_cndmask_b32_e32 v214, v208, v84, vcc
	v_mov_b32_e32 v224, v223
	v_cvt_pk_bf16_f32 v84, v233, v235
	v_cvt_pk_bf16_f32 v85, v231, v234
	v_cvt_pk_bf16_f32 v86, v229, v232
	v_cndmask_b32_e32 v211, v208, v87, vcc
	v_cndmask_b32_e32 v215, v208, v83, vcc
	v_cndmask_b32_e32 v216, v208, v82, vcc
	v_cndmask_b32_e32 v217, v208, v81, vcc
	v_permlane32_swap_b32_e32 v223, v224
	v_cvt_pk_bf16_f32 v87, v228, v230
	v_permlane32_swap_b32_e32 v84, v86
	v_cvt_pk_bf16_f32 v154, v225, v227
	v_cvt_pk_bf16_f32 v155, v221, v226
	v_cvt_pk_bf16_f32 v156, v219, v222
	v_cvt_pk_bf16_f32 v157, v195, v220
	v_cvt_pk_bf16_f32 v202, v64, v65
	v_cvt_pk_bf16_f32 v203, v66, v67
	v_cvt_pk_bf16_f32 v204, v68, v69
	v_cvt_pk_bf16_f32 v205, v70, v71
	v_cvt_pk_bf16_f32 v226, v72, v73
	v_cvt_pk_bf16_f32 v227, v74, v75
	v_cvt_pk_bf16_f32 v228, v76, v77
	v_cvt_pk_bf16_f32 v229, v78, v79
	v_permlane32_swap_b32_e32 v85, v87
	v_permlane32_swap_b32_e32 v154, v156
	v_permlane32_swap_b32_e32 v155, v157
	v_permlane32_swap_b32_e32 v202, v204
	v_permlane32_swap_b32_e32 v203, v205
	v_permlane32_swap_b32_e32 v226, v228
	v_permlane32_swap_b32_e32 v227, v229
	ds_read_b64_tr_b16 v[138:139], v162 offset:0
	ds_read_b64_tr_b16 v[140:141], v162 offset:0x800
	ds_read_b64_tr_b16 v[230:231], v162 offset:0x1000
	ds_read_b64_tr_b16 v[232:233], v162 offset:0x1800
	ds_read_b64_tr_b16 v[234:235], v162 offset:0x2000
	ds_read_b64_tr_b16 v[236:237], v162 offset:0x2800
	ds_read_b64_tr_b16 v[238:239], v162 offset:0x3000
	ds_read_b64_tr_b16 v[240:241], v162 offset:0x3800
	s_waitcnt lgkmcnt(0)
	s_nop 0
	v_mfma_f32_32x32x16_bf16 v[0:15], v[84:87], v[138:141], v[0:15]
	ds_read_b64_tr_b16 v[138:139], v162 offset:0x200
	ds_read_b64_tr_b16 v[140:141], v162 offset:0xa00
	v_mfma_f32_32x32x16_bf16 v[0:15], v[154:157], v[230:233], v[0:15]
	ds_read_b64_tr_b16 v[230:231], v162 offset:0x1200
	ds_read_b64_tr_b16 v[232:233], v162 offset:0x1a00
	v_mfma_f32_32x32x16_bf16 v[0:15], v[202:205], v[234:237], v[0:15]
	ds_read_b64_tr_b16 v[234:235], v162 offset:0x2200
	ds_read_b64_tr_b16 v[236:237], v162 offset:0x2a00
	v_mfma_f32_32x32x16_bf16 v[0:15], v[226:229], v[238:241], v[0:15]
	ds_read_b64_tr_b16 v[238:239], v162 offset:0x3200
	ds_read_b64_tr_b16 v[240:241], v162 offset:0x3a00
	s_waitcnt lgkmcnt(0)
	v_mfma_f32_32x32x16_bf16 v[48:63], v[84:87], v[138:141], v[48:63]
	ds_read_b64_tr_b16 v[138:139], v162 offset:0x400
	ds_read_b64_tr_b16 v[140:141], v162 offset:0xc00
	v_mfma_f32_32x32x16_bf16 v[48:63], v[154:157], v[230:233], v[48:63]
	ds_read_b64_tr_b16 v[230:231], v162 offset:0x1400
	ds_read_b64_tr_b16 v[232:233], v162 offset:0x1c00
	v_mfma_f32_32x32x16_bf16 v[48:63], v[202:205], v[234:237], v[48:63]
	ds_read_b64_tr_b16 v[234:235], v162 offset:0x2400
	ds_read_b64_tr_b16 v[236:237], v162 offset:0x2c00
	v_mfma_f32_32x32x16_bf16 v[48:63], v[226:229], v[238:241], v[48:63]
	ds_read_b64_tr_b16 v[238:239], v162 offset:0x3400
	ds_read_b64_tr_b16 v[240:241], v162 offset:0x3c00
	s_waitcnt lgkmcnt(0)
	v_mfma_f32_32x32x16_bf16 v[32:47], v[84:87], v[138:141], v[32:47]
	ds_read_b64_tr_b16 v[138:139], v162 offset:0x600
	ds_read_b64_tr_b16 v[140:141], v162 offset:0xe00
	v_mfma_f32_32x32x16_bf16 v[32:47], v[154:157], v[230:233], v[32:47]
	ds_read_b64_tr_b16 v[230:231], v162 offset:0x1600
	ds_read_b64_tr_b16 v[232:233], v162 offset:0x1e00
	v_mfma_f32_32x32x16_bf16 v[32:47], v[202:205], v[234:237], v[32:47]
	ds_read_b64_tr_b16 v[234:235], v162 offset:0x2600
	ds_read_b64_tr_b16 v[236:237], v162 offset:0x2e00
	v_mfma_f32_32x32x16_bf16 v[32:47], v[226:229], v[238:241], v[32:47]
	ds_read_b64_tr_b16 v[238:239], v162 offset:0x3600
	ds_read_b64_tr_b16 v[240:241], v162 offset:0x3e00
	s_waitcnt lgkmcnt(0)
	v_mfma_f32_32x32x16_bf16 v[16:31], v[84:87], v[138:141], v[16:31]
	v_max_f32_e32 v84, v217, v217
	v_max_f32_e32 v85, v218, v218
	v_max_f32_e32 v84, v85, v84
	v_max3_f32 v84, v84, v216, v215
	v_max3_f32 v84, v84, v214, v213
	v_max3_f32 v84, v84, v212, v211
	v_max3_f32 v84, v84, v210, v199
	v_mfma_f32_32x32x16_bf16 v[16:31], v[154:157], v[230:233], v[16:31]
	v_max3_f32 v84, v84, v198, v197
	v_max3_f32 v84, v84, v153, v152
	v_max3_f32 v84, v84, v151, v150
	v_max3_f32 v84, v84, v148, v149
	v_max3_f32 v84, v84, v146, v147
	v_max3_f32 v84, v84, v144, v145
	v_max3_f32 v84, v84, v142, v143
	v_mfma_f32_32x32x16_bf16 v[16:31], v[202:205], v[234:237], v[16:31]
	v_max3_f32 v84, v84, v94, v95
	v_max3_f32 v84, v84, v92, v93
	v_max3_f32 v84, v84, v90, v91
	v_max3_f32 v84, v84, v88, v89
	v_mov_b32_e32 v85, v84
	s_nop 1
	v_permlane32_swap_b32_e32 v84, v85
	v_mfma_f32_32x32x16_bf16 v[16:31], v[226:229], v[238:241], v[16:31]
	v_max_f32_e32 v85, v85, v85
	v_max_f32_e32 v84, v84, v84
	v_max_f32_e32 v84, v84, v85
	v_sub_f32_e32 v85, v84, v165
	v_cmp_ge_f32_e32 vcc, s21, v85
	v_mov_b32_e32 v195, 1.0
	s_cmp_eq_u64 vcc, exec
	s_cbranch_scc0 .LBB0_751

.Latt1_738:
	v_readfirstlane_b32 s16, v134
	v_readfirstlane_b32 s17, v135
	s_lshl_b32 s3, s78, 10
	s_add_u32 s16, s16, 0x33080000
	s_addc_u32 s17, s17, 0
	s_add_i32 m0, s3, 0x8000
	s_nop 0
	global_load_lds_dwordx4 v166, s[16:17]
	s_add_u32 s16, s16, 0x20000
	s_addc_u32 s17, s17, 0
	s_add_i32 m0, s3, 0xa000
	s_nop 0
	global_load_lds_dwordx4 v166, s[16:17]
	v_readfirstlane_b32 s16, v132
	v_readfirstlane_b32 s17, v133
	s_add_u32 s16, s16, 0x2f804000
	s_addc_u32 s17, s17, 0
	s_add_i32 m0, s3, 0x10000
	s_nop 0
	global_load_lds_dwordx4 v168, s[16:17]
	v_readfirstlane_b32 s16, v134
	v_readfirstlane_b32 s17, v135
	s_lshl_b32 s3, s78, 14
	s_sub_u32 s16, s16, s3
	s_subb_u32 s17, s17, 0
	s_add_u32 s16, s16, 0x33040100
	s_addc_u32 s17, s17, 0
	s_lshl_b32 s3, s78, 10
	s_add_i32 m0, s3, 0x4000
	s_nop 0
	global_load_lds_dwordx4 v167, s[16:17]
	s_add_u32 s16, s16, 0x20000
	s_addc_u32 s17, s17, 0
	s_add_i32 m0, s3, 0x6000
	s_nop 0
	global_load_lds_dwordx4 v167, s[16:17]
	v_add_f32_e32 v80, 0, v220
	v_add_f32_e32 v80, v222, v80
	v_add_f32_e32 v80, v218, v80
	v_add_f32_e32 v80, v221, v80
	v_add_f32_e32 v80, v216, v80
	v_add_f32_e32 v80, v219, v80
	v_add_f32_e32 v80, v215, v80
	v_add_f32_e32 v80, v217, v80
	v_add_f32_e32 v80, v212, v80
	v_add_f32_e32 v80, v214, v80
	v_add_f32_e32 v80, v210, v80
	v_add_f32_e32 v80, v213, v80
	v_exp_f32_e32 v64, v148
	v_add_f32_e32 v80, v198, v80
	v_exp_f32_e32 v65, v149
	v_add_f32_e32 v80, v211, v80
	v_exp_f32_e32 v66, v146
	v_add_f32_e32 v80, v197, v80
	v_exp_f32_e32 v67, v147
	v_add_f32_e32 v80, v199, v80
	v_exp_f32_e32 v68, v144
	v_add_f32_e32 v80, v64, v80
	v_exp_f32_e32 v69, v145
	v_add_f32_e32 v80, v65, v80
	v_exp_f32_e32 v70, v140
	v_add_f32_e32 v80, v66, v80
	v_exp_f32_e32 v71, v141
	v_add_f32_e32 v80, v67, v80
	v_exp_f32_e32 v72, v138
	v_add_f32_e32 v80, v68, v80
	v_exp_f32_e32 v73, v139
	v_add_f32_e32 v80, v69, v80
	v_exp_f32_e32 v74, v152
	v_add_f32_e32 v80, v70, v80
	v_exp_f32_e32 v75, v153
	v_add_f32_e32 v80, v71, v80
	v_exp_f32_e32 v76, v150
	v_add_f32_e32 v80, v72, v80
	v_exp_f32_e32 v77, v151
	v_add_f32_e32 v80, v73, v80
	v_exp_f32_e32 v78, v142
	v_add_f32_e32 v80, v74, v80
	v_exp_f32_e32 v79, v143
	v_add_f32_e32 v80, v75, v80
	v_add_f32_e32 v80, v76, v80
	v_add_f32_e32 v80, v77, v80
	v_add_f32_e32 v80, v78, v80
	v_add_f32_e32 v246, v79, v80
	v_cvt_pk_bf16_f32 v142, v212, v214
	v_cvt_pk_bf16_f32 v143, v210, v213
	v_cvt_pk_bf16_f32 v144, v198, v211
	v_cvt_pk_bf16_f32 v145, v197, v199
	v_cvt_pk_bf16_f32 v146, v64, v65
	v_cvt_pk_bf16_f32 v147, v66, v67
	v_cvt_pk_bf16_f32 v148, v68, v69
	v_cvt_pk_bf16_f32 v149, v70, v71
	v_cvt_pk_bf16_f32 v150, v72, v73
	v_cvt_pk_bf16_f32 v151, v74, v75
	v_cvt_pk_bf16_f32 v152, v76, v77
	v_cvt_pk_bf16_f32 v153, v78, v79
	v_permlane32_swap_b32_e32 v142, v144
	v_permlane32_swap_b32_e32 v143, v145
	v_permlane32_swap_b32_e32 v146, v148
	v_permlane32_swap_b32_e32 v147, v149
	v_permlane32_swap_b32_e32 v150, v152
	v_permlane32_swap_b32_e32 v151, v153
	s_add_i32 s2, s26, -1
	ds_read_b128 v[64:67], v170 offset:49152
	ds_read_b128 v[68:71], v170 offset:57344
	ds_read_b128 v[154:157], v171 offset:49152
	ds_read_b128 v[202:205], v171 offset:57344
	ds_read_b128 v[224:227], v172 offset:49152
	ds_read_b128 v[228:231], v172 offset:57344
	s_add_i32 s3, 0, 0x12000
	v_add_u32_e32 v189, s3, v178
	v_add_u32_e32 v190, s3, v180
	v_add_u32_e32 v191, s3, v182
	v_add_u32_e32 v192, s3, v184
	s_cmp_gt_u32 s2, s27
	s_cselect_b64 vcc, -1, 0
	s_waitcnt lgkmcnt(5)
	v_mfma_f32_32x32x16_bf16 v[80:95], v[64:67], v[126:129], 0
	s_waitcnt lgkmcnt(4)
	v_mfma_f32_32x32x16_bf16 v[64:79], v[68:71], v[126:129], 0
	s_waitcnt lgkmcnt(3)
	v_mfma_f32_32x32x16_bf16 v[80:95], v[154:157], v[122:125], v[80:95]
	ds_read_b128 v[154:157], v173 offset:49152
	s_waitcnt lgkmcnt(3)
	v_mfma_f32_32x32x16_bf16 v[64:79], v[202:205], v[122:125], v[64:79]
	ds_read_b128 v[202:205], v173 offset:57344
	s_waitcnt lgkmcnt(3)
	v_mfma_f32_32x32x16_bf16 v[80:95], v[224:227], v[118:121], v[80:95]
	ds_read_b128 v[224:227], v174 offset:49152
	s_waitcnt lgkmcnt(3)
	v_mfma_f32_32x32x16_bf16 v[64:79], v[228:231], v[118:121], v[64:79]
	ds_read_b128 v[228:231], v174 offset:57344
	s_waitcnt lgkmcnt(3)
	v_mfma_f32_32x32x16_bf16 v[80:95], v[154:157], v[114:117], v[80:95]
	ds_read_b128 v[154:157], v175 offset:49152
	s_waitcnt lgkmcnt(3)
	v_mfma_f32_32x32x16_bf16 v[64:79], v[202:205], v[114:117], v[64:79]
	ds_read_b128 v[202:205], v175 offset:57344
	s_waitcnt lgkmcnt(3)
	v_mfma_f32_32x32x16_bf16 v[80:95], v[224:227], v[110:113], v[80:95]
	ds_read_b128 v[224:227], v176 offset:49152
	s_waitcnt lgkmcnt(3)
	v_mfma_f32_32x32x16_bf16 v[64:79], v[228:231], v[110:113], v[64:79]
	ds_read_b128 v[228:231], v176 offset:57344
	s_waitcnt lgkmcnt(3)
	v_mfma_f32_32x32x16_bf16 v[80:95], v[154:157], v[106:109], v[80:95]
	ds_read_b128 v[154:157], v177 offset:49152
	s_waitcnt lgkmcnt(3)
	v_mfma_f32_32x32x16_bf16 v[64:79], v[202:205], v[106:109], v[64:79]
	ds_read_b128 v[202:205], v177 offset:57344
	s_waitcnt lgkmcnt(3)
	v_mfma_f32_32x32x16_bf16 v[80:95], v[224:227], v[102:105], v[80:95]
	ds_read_b128 v[232:235], v189
	ds_read_b128 v[236:239], v189 offset:4096
	ds_read_b128 v[240:243], v163
	s_waitcnt lgkmcnt(5)
	v_mfma_f32_32x32x16_bf16 v[64:79], v[228:231], v[102:105], v[64:79]
	s_waitcnt lgkmcnt(4)
	v_mfma_f32_32x32x16_bf16 v[80:95], v[154:157], v[98:101], v[80:95]
	ds_read_b128 v[224:227], v190
	ds_read_b128 v[228:231], v190 offset:4096
	ds_read_b128 v[154:157], v163 offset:1024
	s_waitcnt lgkmcnt(6)
	v_mfma_f32_32x32x16_bf16 v[64:79], v[202:205], v[98:101], v[64:79]
	s_waitcnt lgkmcnt(3)
	v_mfma_f32_32x32x16_bf16 v[80:95], v[232:235], v[240:243], v[80:95]
	s_waitcnt lgkmcnt(3)
	v_mfma_f32_32x32x16_bf16 v[64:79], v[236:239], v[240:243], v[64:79]
	ds_read_b128 v[232:235], v191
	ds_read_b128 v[236:239], v191 offset:4096
	ds_read_b128 v[240:243], v163 offset:2048
	s_waitcnt lgkmcnt(3)
	v_mfma_f32_32x32x16_bf16 v[80:95], v[224:227], v[154:157], v[80:95]
	s_waitcnt lgkmcnt(3)
	v_mfma_f32_32x32x16_bf16 v[64:79], v[228:231], v[154:157], v[64:79]
	ds_read_b128 v[224:227], v192
	ds_read_b128 v[228:231], v192 offset:4096
	ds_read_b128 v[154:157], v163 offset:3072
	s_waitcnt lgkmcnt(3)
	v_mfma_f32_32x32x16_bf16 v[80:95], v[232:235], v[240:243], v[80:95]
	s_waitcnt lgkmcnt(3)
	v_mfma_f32_32x32x16_bf16 v[64:79], v[236:239], v[240:243], v[64:79]
	s_waitcnt lgkmcnt(0)
	v_mfma_f32_32x32x16_bf16 v[80:95], v[224:227], v[154:157], v[80:95]
	s_waitcnt lgkmcnt(0)
	v_mfma_f32_32x32x16_bf16 v[64:79], v[228:231], v[154:157], v[64:79]
	s_nop 10
	v_cndmask_b32_e32 v240, v80, v208, vcc
	v_cndmask_b32_e32 v244, v64, v208, vcc
	v_cndmask_b32_e32 v245, v65, v208, vcc
	v_cndmask_b32_e32 v242, v66, v208, vcc
	v_cndmask_b32_e32 v243, v67, v208, vcc
	v_cndmask_b32_e32 v238, v68, v208, vcc
	v_cndmask_b32_e32 v239, v69, v208, vcc
	v_cndmask_b32_e32 v234, v70, v208, vcc
	v_cndmask_b32_e32 v235, v71, v208, vcc
	v_cndmask_b32_e32 v230, v72, v208, vcc
	v_cndmask_b32_e32 v231, v73, v208, vcc
	v_cndmask_b32_e32 v227, v74, v208, vcc
	v_cndmask_b32_e32 v228, v75, v208, vcc
	v_cndmask_b32_e32 v225, v76, v208, vcc
	v_cndmask_b32_e32 v195, v90, v208, vcc
	v_cndmask_b32_e32 v90, v77, v208, vcc
	v_cndmask_b32_e32 v223, v88, v208, vcc
	v_cndmask_b32_e32 v88, v78, v208, vcc
	v_cndmask_b32_e32 v224, v89, v208, vcc
	v_cndmask_b32_e32 v89, v79, v208, vcc
	v_cndmask_b32_e32 v226, v86, v208, vcc
	v_cndmask_b32_e32 v232, v84, v208, vcc
	v_cndmask_b32_e32 v233, v85, v208, vcc
	v_cndmask_b32_e32 v94, v94, v208, vcc
	v_cndmask_b32_e32 v95, v95, v208, vcc
	v_cndmask_b32_e32 v92, v92, v208, vcc
	v_cndmask_b32_e32 v93, v93, v208, vcc
	v_cndmask_b32_e32 v91, v91, v208, vcc
	v_cndmask_b32_e32 v229, v87, v208, vcc
	v_cndmask_b32_e32 v236, v82, v208, vcc
	v_cndmask_b32_e32 v237, v83, v208, vcc
	v_cndmask_b32_e32 v241, v81, v208, vcc
	v_mov_b32_e32 v193, v246
	v_mov_b32_e32 v194, v246
	v_cvt_pk_bf16_f32 v84, v220, v222
	v_cvt_pk_bf16_f32 v85, v218, v221
	v_cvt_pk_bf16_f32 v86, v216, v219
	v_cvt_pk_bf16_f32 v87, v215, v217
	s_nop 1
	v_permlane32_swap_b32_e32 v193, v194
	v_permlane32_swap_b32_e32 v84, v86
	v_permlane32_swap_b32_e32 v85, v87
	ds_read_b64_tr_b16 v[154:155], v164 offset:0
	ds_read_b64_tr_b16 v[156:157], v164 offset:0x800
	ds_read_b64_tr_b16 v[196:197], v164 offset:0x1000
	ds_read_b64_tr_b16 v[198:199], v164 offset:0x1800
	ds_read_b64_tr_b16 v[202:203], v164 offset:0x2000
	ds_read_b64_tr_b16 v[204:205], v164 offset:0x2800
	ds_read_b64_tr_b16 v[210:211], v164 offset:0x3000
	ds_read_b64_tr_b16 v[212:213], v164 offset:0x3800
	s_waitcnt lgkmcnt(0)
	s_nop 0
	v_mfma_f32_32x32x16_bf16 v[0:15], v[84:87], v[154:157], v[0:15]
	ds_read_b64_tr_b16 v[154:155], v164 offset:0x200
	ds_read_b64_tr_b16 v[156:157], v164 offset:0xa00
	v_mfma_f32_32x32x16_bf16 v[0:15], v[142:145], v[196:199], v[0:15]
	ds_read_b64_tr_b16 v[196:197], v164 offset:0x1200
	ds_read_b64_tr_b16 v[198:199], v164 offset:0x1a00
	v_mfma_f32_32x32x16_bf16 v[0:15], v[146:149], v[202:205], v[0:15]
	ds_read_b64_tr_b16 v[202:203], v164 offset:0x2200
	ds_read_b64_tr_b16 v[204:205], v164 offset:0x2a00
	v_mfma_f32_32x32x16_bf16 v[0:15], v[150:153], v[210:213], v[0:15]
	ds_read_b64_tr_b16 v[210:211], v164 offset:0x3200
	ds_read_b64_tr_b16 v[212:213], v164 offset:0x3a00
	s_waitcnt lgkmcnt(0)
	v_mfma_f32_32x32x16_bf16 v[48:63], v[84:87], v[154:157], v[48:63]
	ds_read_b64_tr_b16 v[154:155], v164 offset:0x400
	ds_read_b64_tr_b16 v[156:157], v164 offset:0xc00
	v_mfma_f32_32x32x16_bf16 v[48:63], v[142:145], v[196:199], v[48:63]
	ds_read_b64_tr_b16 v[196:197], v164 offset:0x1400
	ds_read_b64_tr_b16 v[198:199], v164 offset:0x1c00
	v_mfma_f32_32x32x16_bf16 v[48:63], v[146:149], v[202:205], v[48:63]
	ds_read_b64_tr_b16 v[202:203], v164 offset:0x2400
	ds_read_b64_tr_b16 v[204:205], v164 offset:0x2c00
	v_mfma_f32_32x32x16_bf16 v[48:63], v[150:153], v[210:213], v[48:63]
	ds_read_b64_tr_b16 v[210:211], v164 offset:0x3400
	ds_read_b64_tr_b16 v[212:213], v164 offset:0x3c00
	s_waitcnt lgkmcnt(0)
	v_mfma_f32_32x32x16_bf16 v[32:47], v[84:87], v[154:157], v[32:47]
	ds_read_b64_tr_b16 v[154:155], v164 offset:0x600
	ds_read_b64_tr_b16 v[156:157], v164 offset:0xe00
	v_mfma_f32_32x32x16_bf16 v[32:47], v[142:145], v[196:199], v[32:47]
	ds_read_b64_tr_b16 v[196:197], v164 offset:0x1600
	ds_read_b64_tr_b16 v[198:199], v164 offset:0x1e00
	v_mfma_f32_32x32x16_bf16 v[32:47], v[146:149], v[202:205], v[32:47]
	ds_read_b64_tr_b16 v[202:203], v164 offset:0x2600
	ds_read_b64_tr_b16 v[204:205], v164 offset:0x2e00
	v_mfma_f32_32x32x16_bf16 v[32:47], v[150:153], v[210:213], v[32:47]
	ds_read_b64_tr_b16 v[210:211], v164 offset:0x3600
	ds_read_b64_tr_b16 v[212:213], v164 offset:0x3e00
	s_waitcnt lgkmcnt(0)
	v_mfma_f32_32x32x16_bf16 v[16:31], v[84:87], v[154:157], v[16:31]
	v_max_f32_e32 v84, v241, v241
	v_max_f32_e32 v85, v240, v240
	v_max_f32_e32 v84, v85, v84
	v_max3_f32 v84, v84, v236, v237
	v_max3_f32 v84, v84, v232, v233
	v_max3_f32 v84, v84, v226, v229
	v_max3_f32 v84, v84, v223, v224
	v_mfma_f32_32x32x16_bf16 v[16:31], v[142:145], v[196:199], v[16:31]
	v_max3_f32 v84, v84, v195, v91
	v_max3_f32 v84, v84, v92, v93
	v_max3_f32 v84, v84, v94, v95
	v_max3_f32 v84, v84, v244, v245
	v_max3_f32 v84, v84, v242, v243
	v_max3_f32 v84, v84, v238, v239
	v_max3_f32 v84, v84, v234, v235
	v_mfma_f32_32x32x16_bf16 v[16:31], v[146:149], v[202:205], v[16:31]
	v_max3_f32 v84, v84, v230, v231
	v_max3_f32 v84, v84, v227, v228
	v_max3_f32 v84, v84, v225, v90
	v_max3_f32 v84, v84, v88, v89
	v_mov_b32_e32 v85, v84
	s_nop 1
	v_permlane32_swap_b32_e32 v84, v85
	v_mfma_f32_32x32x16_bf16 v[16:31], v[150:153], v[210:213], v[16:31]
	v_max_f32_e32 v85, v85, v85
	v_max_f32_e32 v84, v84, v84
	v_max_f32_e32 v84, v84, v85
	v_sub_f32_e32 v85, v84, v165
	v_cmp_ge_f32_e32 vcc, s21, v85
	v_mov_b32_e32 v196, 1.0
	s_cmp_eq_u64 vcc, exec
	s_cbranch_scc0 .Latt1_750

.Latt1_743:
	v_mul_f32_e32 v136, 0xbdd53b94, v165
	v_fmamk_f32 v78, v94, 0x3dd53b94, v136
	v_fmamk_f32 v74, v195, 0x3dd53b94, v136
	v_exp_f32_e32 v195, v78
	v_fmamk_f32 v64, v240, 0x3dd53b94, v136
	v_fmamk_f32 v65, v241, 0x3dd53b94, v136
	v_fmamk_f32 v66, v236, 0x3dd53b94, v136
	v_fmamk_f32 v67, v237, 0x3dd53b94, v136
	v_fmamk_f32 v68, v232, 0x3dd53b94, v136
	v_fmamk_f32 v69, v233, 0x3dd53b94, v136
	v_fmamk_f32 v70, v226, 0x3dd53b94, v136
	v_fmamk_f32 v71, v229, 0x3dd53b94, v136
	v_fmamk_f32 v72, v223, 0x3dd53b94, v136
	v_fmamk_f32 v73, v224, 0x3dd53b94, v136
	v_fmamk_f32 v75, v91, 0x3dd53b94, v136
	v_fmamk_f32 v76, v92, 0x3dd53b94, v136
	v_fmamk_f32 v77, v93, 0x3dd53b94, v136
	v_fmamk_f32 v79, v95, 0x3dd53b94, v136
	v_fmamk_f32 v223, v244, 0x3dd53b94, v136
	v_fmamk_f32 v224, v245, 0x3dd53b94, v136
	v_fmamk_f32 v236, v242, 0x3dd53b94, v136
	v_fmamk_f32 v237, v243, 0x3dd53b94, v136
	v_fmamk_f32 v238, v238, 0x3dd53b94, v136
	v_fmamk_f32 v239, v239, 0x3dd53b94, v136
	v_fmamk_f32 v240, v234, 0x3dd53b94, v136
	v_fmamk_f32 v241, v235, 0x3dd53b94, v136
	v_fmamk_f32 v242, v230, 0x3dd53b94, v136
	v_fmamk_f32 v243, v231, 0x3dd53b94, v136
	v_fmamk_f32 v244, v227, 0x3dd53b94, v136
	v_fmamk_f32 v245, v228, 0x3dd53b94, v136
	v_fmamk_f32 v246, v225, 0x3dd53b94, v136
	v_exp_f32_e32 v233, v64
	v_exp_f32_e32 v235, v65
	v_exp_f32_e32 v231, v66
	v_exp_f32_e32 v234, v67
	v_exp_f32_e32 v229, v68
	v_exp_f32_e32 v232, v69
	v_exp_f32_e32 v228, v70
	v_exp_f32_e32 v230, v71
	v_exp_f32_e32 v225, v72
	v_exp_f32_e32 v227, v73
	v_exp_f32_e32 v221, v74
	v_exp_f32_e32 v226, v75
	v_exp_f32_e32 v219, v76
	v_exp_f32_e32 v222, v77
	v_exp_f32_e32 v220, v79
	v_fmamk_f32 v247, v90, 0x3dd53b94, v136
	v_fmamk_f32 v248, v88, 0x3dd53b94, v136
	v_fmamk_f32 v202, v89, 0x3dd53b94, v136
	s_waitcnt vmcnt(0) lgkmcnt(0)
	s_barrier
	v_readfirstlane_b32 s16, v134
	v_readfirstlane_b32 s17, v135
	s_lshl_b32 s3, s78, 10
	s_add_u32 s16, s16, 0x330c0000
	s_addc_u32 s17, s17, 0
	s_add_i32 m0, s3, 0xc000
	s_nop 0
	global_load_lds_dwordx4 v166, s[16:17]
	s_add_u32 s16, s16, 0x20000
	s_addc_u32 s17, s17, 0
	s_add_i32 m0, s3, 0xe000
	s_nop 0
	global_load_lds_dwordx4 v166, s[16:17]
	v_readfirstlane_b32 s16, v132
	v_readfirstlane_b32 s17, v133
	s_add_u32 s16, s16, 0x2f806000
	s_addc_u32 s17, s17, 0
	s_add_i32 m0, s3, 0x12000
	s_nop 0
	global_load_lds_dwordx4 v168, s[16:17]
	v_readfirstlane_b32 s16, v134
	v_readfirstlane_b32 s17, v135
	s_lshl_b32 s3, s78, 14
	s_sub_u32 s16, s16, s3
	s_subb_u32 s17, s17, 0
	s_add_u32 s16, s16, 0x33080100
	s_addc_u32 s17, s17, 0
	s_lshl_b32 s3, s78, 10
	s_add_i32 m0, s3, 0x0
	s_nop 0
	global_load_lds_dwordx4 v167, s[16:17]
	s_add_u32 s16, s16, 0x20000
	s_addc_u32 s17, s17, 0
	s_add_i32 m0, s3, 0x2000
	s_nop 0
	global_load_lds_dwordx4 v167, s[16:17]
	v_add_f32_e32 v80, 0, v233
	v_add_f32_e32 v80, v235, v80
	v_add_f32_e32 v80, v231, v80
	v_add_f32_e32 v80, v234, v80
	v_add_f32_e32 v80, v229, v80
	v_add_f32_e32 v80, v232, v80
	v_add_f32_e32 v80, v228, v80
	v_add_f32_e32 v80, v230, v80
	v_add_f32_e32 v80, v225, v80
	v_add_f32_e32 v80, v227, v80
	v_add_f32_e32 v80, v221, v80
	v_add_f32_e32 v80, v226, v80
	v_exp_f32_e32 v64, v223
	v_add_f32_e32 v80, v219, v80
	v_exp_f32_e32 v65, v224
	v_add_f32_e32 v80, v222, v80
	v_exp_f32_e32 v66, v236
	v_add_f32_e32 v80, v195, v80
	v_exp_f32_e32 v67, v237
	v_add_f32_e32 v80, v220, v80
	v_exp_f32_e32 v68, v238
	v_add_f32_e32 v80, v64, v80
	v_exp_f32_e32 v69, v239
	v_add_f32_e32 v80, v65, v80
	v_exp_f32_e32 v70, v240
	v_add_f32_e32 v80, v66, v80
	v_exp_f32_e32 v71, v241
	v_add_f32_e32 v80, v67, v80
	v_exp_f32_e32 v72, v242
	v_add_f32_e32 v80, v68, v80
	v_exp_f32_e32 v73, v243
	v_add_f32_e32 v80, v69, v80
	v_exp_f32_e32 v74, v244
	v_add_f32_e32 v80, v70, v80
	v_exp_f32_e32 v75, v245
	v_add_f32_e32 v80, v71, v80
	v_exp_f32_e32 v76, v246
	v_add_f32_e32 v80, v72, v80
	v_exp_f32_e32 v77, v247
	v_add_f32_e32 v80, v73, v80
	v_exp_f32_e32 v78, v248
	v_add_f32_e32 v80, v74, v80
	v_exp_f32_e32 v79, v202
	v_add_f32_e32 v80, v75, v80
	v_add_f32_e32 v80, v76, v80
	v_add_f32_e32 v80, v77, v80
	v_add_f32_e32 v80, v78, v80
	v_add_f32_e32 v223, v79, v80
	v_mov_b32_e32 v224, v223
	v_cvt_pk_bf16_f32 v247, v229, v232
	v_cvt_pk_bf16_f32 v248, v228, v230
	v_cvt_pk_bf16_f32 v154, v225, v227
	v_cvt_pk_bf16_f32 v155, v221, v226
	v_cvt_pk_bf16_f32 v156, v219, v222
	v_cvt_pk_bf16_f32 v157, v195, v220
	v_cvt_pk_bf16_f32 v202, v64, v65
	v_cvt_pk_bf16_f32 v203, v66, v67
	v_cvt_pk_bf16_f32 v204, v68, v69
	v_cvt_pk_bf16_f32 v205, v70, v71
	v_cvt_pk_bf16_f32 v226, v72, v73
	v_cvt_pk_bf16_f32 v227, v74, v75
	v_cvt_pk_bf16_f32 v228, v76, v77
	v_cvt_pk_bf16_f32 v229, v78, v79
	v_permlane32_swap_b32_e32 v154, v156
	v_permlane32_swap_b32_e32 v155, v157
	v_permlane32_swap_b32_e32 v202, v204
	v_permlane32_swap_b32_e32 v203, v205
	v_permlane32_swap_b32_e32 v226, v228
	v_permlane32_swap_b32_e32 v227, v229
	v_permlane32_swap_b32_e32 v223, v224
	ds_read_b128 v[64:67], v170 offset:32768
	ds_read_b128 v[68:71], v170 offset:40960
	ds_read_b128 v[142:145], v171 offset:32768
	ds_read_b128 v[146:149], v171 offset:40960
	ds_read_b128 v[150:153], v172 offset:32768
	s_cmp_lt_u32 s2, s27
	s_cselect_b64 vcc, -1, 0
	s_waitcnt lgkmcnt(4)
	v_mfma_f32_32x32x16_bf16 v[80:95], v[64:67], v[126:129], 0
	s_waitcnt lgkmcnt(3)
	v_mfma_f32_32x32x16_bf16 v[64:79], v[68:71], v[126:129], 0
	s_waitcnt lgkmcnt(2)
	v_mfma_f32_32x32x16_bf16 v[80:95], v[142:145], v[122:125], v[80:95]
	ds_read_b128 v[142:145], v172 offset:40960
	s_waitcnt lgkmcnt(2)
	v_mfma_f32_32x32x16_bf16 v[64:79], v[146:149], v[122:125], v[64:79]
	ds_read_b128 v[146:149], v173 offset:32768
	s_waitcnt lgkmcnt(2)
	v_mfma_f32_32x32x16_bf16 v[80:95], v[150:153], v[118:121], v[80:95]
	ds_read_b128 v[150:153], v173 offset:40960
	s_waitcnt lgkmcnt(2)
	v_mfma_f32_32x32x16_bf16 v[64:79], v[142:145], v[118:121], v[64:79]
	ds_read_b128 v[142:145], v174 offset:32768
	s_waitcnt lgkmcnt(2)
	v_mfma_f32_32x32x16_bf16 v[80:95], v[146:149], v[114:117], v[80:95]
	ds_read_b128 v[146:149], v174 offset:40960
	s_waitcnt lgkmcnt(2)
	v_mfma_f32_32x32x16_bf16 v[64:79], v[150:153], v[114:117], v[64:79]
	ds_read_b128 v[150:153], v175 offset:32768
	s_waitcnt lgkmcnt(2)
	v_mfma_f32_32x32x16_bf16 v[80:95], v[142:145], v[110:113], v[80:95]
	ds_read_b128 v[142:145], v175 offset:40960
	s_waitcnt lgkmcnt(2)
	v_mfma_f32_32x32x16_bf16 v[64:79], v[146:149], v[110:113], v[64:79]
	ds_read_b128 v[146:149], v176 offset:32768
	s_waitcnt lgkmcnt(2)
	v_mfma_f32_32x32x16_bf16 v[80:95], v[150:153], v[106:109], v[80:95]
	ds_read_b128 v[150:153], v176 offset:40960
	s_waitcnt lgkmcnt(2)
	v_mfma_f32_32x32x16_bf16 v[64:79], v[142:145], v[106:109], v[64:79]
	ds_read_b128 v[142:145], v177 offset:32768
	s_waitcnt lgkmcnt(2)
	v_mfma_f32_32x32x16_bf16 v[80:95], v[146:149], v[102:105], v[80:95]
	ds_read_b128 v[146:149], v177 offset:40960
	s_waitcnt lgkmcnt(2)
	v_mfma_f32_32x32x16_bf16 v[64:79], v[150:153], v[102:105], v[64:79]
	ds_read_b128 v[210:213], v179
	ds_read_b128 v[214:217], v179 offset:4096
	ds_read_b128 v[150:153], v163
	s_waitcnt lgkmcnt(4)
	v_mfma_f32_32x32x16_bf16 v[80:95], v[142:145], v[98:101], v[80:95]
	s_waitcnt lgkmcnt(3)
	v_mfma_f32_32x32x16_bf16 v[64:79], v[146:149], v[98:101], v[64:79]
	ds_read_b128 v[142:145], v181
	ds_read_b128 v[146:149], v181 offset:4096
	s_waitcnt lgkmcnt(2)
	v_mfma_f32_32x32x16_bf16 v[80:95], v[210:213], v[150:153], v[80:95]
	s_waitcnt lgkmcnt(2)
	v_mfma_f32_32x32x16_bf16 v[64:79], v[214:217], v[150:153], v[64:79]
	ds_read_b128 v[150:153], v163 offset:1024
	ds_read_b128 v[210:213], v183
	ds_read_b128 v[214:217], v183 offset:4096
	s_waitcnt lgkmcnt(2)
	v_mfma_f32_32x32x16_bf16 v[80:95], v[142:145], v[150:153], v[80:95]
	s_waitcnt lgkmcnt(2)
	v_mfma_f32_32x32x16_bf16 v[64:79], v[146:149], v[150:153], v[64:79]
	ds_read_b128 v[150:153], v163 offset:2048
	ds_read_b128 v[142:145], v185
	ds_read_b128 v[146:149], v185 offset:4096
	s_waitcnt lgkmcnt(2)
	v_mfma_f32_32x32x16_bf16 v[80:95], v[210:213], v[150:153], v[80:95]
	s_waitcnt lgkmcnt(2)
	v_mfma_f32_32x32x16_bf16 v[64:79], v[214:217], v[150:153], v[64:79]
	ds_read_b128 v[150:153], v163 offset:3072
	s_waitcnt lgkmcnt(0)
	v_mfma_f32_32x32x16_bf16 v[80:95], v[142:145], v[150:153], v[80:95]
	s_waitcnt lgkmcnt(0)
	v_mfma_f32_32x32x16_bf16 v[64:79], v[146:149], v[150:153], v[64:79]
	s_nop 10
	v_cndmask_b32_e32 v218, v208, v80, vcc
	v_cndmask_b32_e32 v148, v208, v64, vcc
	v_cndmask_b32_e32 v149, v208, v65, vcc
	v_cndmask_b32_e32 v146, v208, v66, vcc
	v_cndmask_b32_e32 v147, v208, v67, vcc
	v_cndmask_b32_e32 v144, v208, v68, vcc
	v_cndmask_b32_e32 v145, v208, v69, vcc
	v_cndmask_b32_e32 v142, v208, v70, vcc
	v_cndmask_b32_e32 v143, v208, v71, vcc
	v_cndmask_b32_e32 v151, v208, v94, vcc
	v_cndmask_b32_e32 v94, v208, v72, vcc
	v_cndmask_b32_e32 v150, v208, v95, vcc
	v_cndmask_b32_e32 v95, v208, v73, vcc
	v_cndmask_b32_e32 v153, v208, v92, vcc
	v_cndmask_b32_e32 v92, v208, v74, vcc
	v_cndmask_b32_e32 v152, v208, v93, vcc
	v_cndmask_b32_e32 v93, v208, v75, vcc
	v_cndmask_b32_e32 v198, v208, v90, vcc
	v_cndmask_b32_e32 v90, v208, v76, vcc
	v_cndmask_b32_e32 v197, v208, v91, vcc
	v_cndmask_b32_e32 v91, v208, v77, vcc
	v_cndmask_b32_e32 v210, v208, v88, vcc
	v_cndmask_b32_e32 v88, v208, v78, vcc
	v_cndmask_b32_e32 v199, v208, v89, vcc
	v_cndmask_b32_e32 v89, v208, v79, vcc
	v_cndmask_b32_e32 v212, v208, v86, vcc
	v_cndmask_b32_e32 v213, v208, v85, vcc
	v_cndmask_b32_e32 v214, v208, v84, vcc
	v_cndmask_b32_e32 v211, v208, v87, vcc
	v_cndmask_b32_e32 v215, v208, v83, vcc
	v_cndmask_b32_e32 v216, v208, v82, vcc
	v_cndmask_b32_e32 v217, v208, v81, vcc
	v_cvt_pk_bf16_f32 v84, v233, v235
	v_cvt_pk_bf16_f32 v85, v231, v234
	v_mov_b32_e32 v86, v247
	v_mov_b32_e32 v87, v248
	s_nop 1
	v_permlane32_swap_b32_e32 v84, v86
	v_permlane32_swap_b32_e32 v85, v87
	ds_read_b64_tr_b16 v[138:139], v162 offset:0
	ds_read_b64_tr_b16 v[140:141], v162 offset:0x800
	ds_read_b64_tr_b16 v[230:231], v162 offset:0x1000
	ds_read_b64_tr_b16 v[232:233], v162 offset:0x1800
	ds_read_b64_tr_b16 v[234:235], v162 offset:0x2000
	ds_read_b64_tr_b16 v[236:237], v162 offset:0x2800
	ds_read_b64_tr_b16 v[238:239], v162 offset:0x3000
	ds_read_b64_tr_b16 v[240:241], v162 offset:0x3800
	s_waitcnt lgkmcnt(0)
	s_nop 0
	v_mfma_f32_32x32x16_bf16 v[0:15], v[84:87], v[138:141], v[0:15]
	ds_read_b64_tr_b16 v[138:139], v162 offset:0x200
	ds_read_b64_tr_b16 v[140:141], v162 offset:0xa00
	v_mfma_f32_32x32x16_bf16 v[0:15], v[154:157], v[230:233], v[0:15]
	ds_read_b64_tr_b16 v[230:231], v162 offset:0x1200
	ds_read_b64_tr_b16 v[232:233], v162 offset:0x1a00
	v_mfma_f32_32x32x16_bf16 v[0:15], v[202:205], v[234:237], v[0:15]
	ds_read_b64_tr_b16 v[234:235], v162 offset:0x2200
	ds_read_b64_tr_b16 v[236:237], v162 offset:0x2a00
	v_mfma_f32_32x32x16_bf16 v[0:15], v[226:229], v[238:241], v[0:15]
	ds_read_b64_tr_b16 v[238:239], v162 offset:0x3200
	ds_read_b64_tr_b16 v[240:241], v162 offset:0x3a00
	s_waitcnt lgkmcnt(0)
	v_mfma_f32_32x32x16_bf16 v[48:63], v[84:87], v[138:141], v[48:63]
	ds_read_b64_tr_b16 v[138:139], v162 offset:0x400
	ds_read_b64_tr_b16 v[140:141], v162 offset:0xc00
	v_mfma_f32_32x32x16_bf16 v[48:63], v[154:157], v[230:233], v[48:63]
	ds_read_b64_tr_b16 v[230:231], v162 offset:0x1400
	ds_read_b64_tr_b16 v[232:233], v162 offset:0x1c00
	v_mfma_f32_32x32x16_bf16 v[48:63], v[202:205], v[234:237], v[48:63]
	ds_read_b64_tr_b16 v[234:235], v162 offset:0x2400
	ds_read_b64_tr_b16 v[236:237], v162 offset:0x2c00
	v_mfma_f32_32x32x16_bf16 v[48:63], v[226:229], v[238:241], v[48:63]
	ds_read_b64_tr_b16 v[238:239], v162 offset:0x3400
	ds_read_b64_tr_b16 v[240:241], v162 offset:0x3c00
	s_waitcnt lgkmcnt(0)
	v_mfma_f32_32x32x16_bf16 v[32:47], v[84:87], v[138:141], v[32:47]
	ds_read_b64_tr_b16 v[138:139], v162 offset:0x600
	ds_read_b64_tr_b16 v[140:141], v162 offset:0xe00
	v_mfma_f32_32x32x16_bf16 v[32:47], v[154:157], v[230:233], v[32:47]
	ds_read_b64_tr_b16 v[230:231], v162 offset:0x1600
	ds_read_b64_tr_b16 v[232:233], v162 offset:0x1e00
	v_mfma_f32_32x32x16_bf16 v[32:47], v[202:205], v[234:237], v[32:47]
	ds_read_b64_tr_b16 v[234:235], v162 offset:0x2600
	ds_read_b64_tr_b16 v[236:237], v162 offset:0x2e00
	v_mfma_f32_32x32x16_bf16 v[32:47], v[226:229], v[238:241], v[32:47]
	ds_read_b64_tr_b16 v[238:239], v162 offset:0x3600
	ds_read_b64_tr_b16 v[240:241], v162 offset:0x3e00
	s_waitcnt lgkmcnt(0)
	v_mfma_f32_32x32x16_bf16 v[16:31], v[84:87], v[138:141], v[16:31]
	v_max_f32_e32 v84, v217, v217
	v_max_f32_e32 v85, v218, v218
	v_max_f32_e32 v84, v85, v84
	v_max3_f32 v84, v84, v216, v215
	v_max3_f32 v84, v84, v214, v213
	v_max3_f32 v84, v84, v212, v211
	v_max3_f32 v84, v84, v210, v199
	v_mfma_f32_32x32x16_bf16 v[16:31], v[154:157], v[230:233], v[16:31]
	v_max3_f32 v84, v84, v198, v197
	v_max3_f32 v84, v84, v153, v152
	v_max3_f32 v84, v84, v151, v150
	v_max3_f32 v84, v84, v148, v149
	v_max3_f32 v84, v84, v146, v147
	v_max3_f32 v84, v84, v144, v145
	v_max3_f32 v84, v84, v142, v143
	v_mfma_f32_32x32x16_bf16 v[16:31], v[202:205], v[234:237], v[16:31]
	v_max3_f32 v84, v84, v94, v95
	v_max3_f32 v84, v84, v92, v93
	v_max3_f32 v84, v84, v90, v91
	v_max3_f32 v84, v84, v88, v89
	v_mov_b32_e32 v85, v84
	s_nop 1
	v_permlane32_swap_b32_e32 v84, v85
	v_mfma_f32_32x32x16_bf16 v[16:31], v[226:229], v[238:241], v[16:31]
	v_max_f32_e32 v85, v85, v85
	v_max_f32_e32 v84, v84, v84
	v_max_f32_e32 v84, v84, v85
	v_sub_f32_e32 v85, v84, v165
	v_cmp_ge_f32_e32 vcc, s21, v85
	v_mov_b32_e32 v195, 1.0
	s_cmp_eq_u64 vcc, exec
	s_cbranch_scc0 .Latt1_751
